# strategy 7.11: loop-carried pointer updates rotated ahead of the loop-back tile barrier in both attention loops (on top of v41)
# speedup vs baseline: 1.0016x; 1.0016x over previous
.LBB0_449:
	v_add_f32_e32 v101, v179, v164
	ds_read_b128 v[164:167], v168 offset:18528
	s_or_b64 s[4:5], s[6:7], s[4:5]
	v_add_f32_e32 v100, v178, v185
	s_or_b64 s[4:5], s[4:5], s[8:9]
	s_or_b64 s[4:5], s[4:5], s[10:11]
	v_add_f32_e32 v182, v100, v104
	v_add_f32_e32 v183, v101, v105
	s_xor_b32 s8, s48, 2
	v_exp_f32_e32 v64, v64
	v_exp_f32_e32 v65, v65
	s_nop 0
	v_add_f32_e32 v185, v65, v64
	v_cvt_pk_bf16_f32 v64, v64, v65
	v_mfma_f32_32x32x16_bf16 v[100:115], v[96:99], v[148:151], 0
	ds_read_b128 v[178:181], v168 offset:9280
	ds_read_b128 v[186:189], v168 offset:9312
	ds_read_b128 v[190:193], v168 offset:13888
	ds_read_b128 v[194:197], v168 offset:13920
	v_exp_f32_e32 v65, v66
	v_exp_f32_e32 v66, v67
	v_add_f32_e32 v67, v65, v185
	v_add_f32_e32 v67, v66, v67
	v_cvt_pk_bf16_f32 v65, v65, v66
	v_mfma_f32_32x32x16_bf16 v[100:115], v[92:95], v[152:155], v[100:115]
	v_exp_f32_e32 v66, v68
	v_exp_f32_e32 v68, v69
	v_add_f32_e32 v67, v66, v67
	v_cvt_pk_bf16_f32 v66, v66, v68
	v_add_f32_e32 v67, v68, v67
	v_mfma_f32_32x32x16_bf16 v[100:115], v[88:91], v[156:159], v[100:115]
	v_exp_f32_e32 v68, v70
	v_exp_f32_e32 v69, v71
	v_add_f32_e32 v70, v68, v67
	v_cvt_pk_bf16_f32 v67, v68, v69
	v_add_f32_e32 v68, v69, v70
	s_waitcnt lgkmcnt(4)
	v_mfma_f32_32x32x16_bf16 v[100:115], v[164:167], v[160:163], v[100:115]
	v_exp_f32_e32 v69, v72
	v_exp_f32_e32 v70, v73
	v_add_f32_e32 v71, v69, v68
	v_cvt_pk_bf16_f32 v68, v69, v70
	v_add_f32_e32 v69, v70, v71
	s_waitcnt lgkmcnt(0)
	v_mfma_f32_32x32x16_bf16 v[16:31], v[178:181], v[80:83], v[16:31]
	v_exp_f32_e32 v70, v74
	v_exp_f32_e32 v71, v75
	v_add_f32_e32 v72, v70, v69
	v_cvt_pk_bf16_f32 v69, v70, v71
	v_add_f32_e32 v70, v71, v72
	v_mfma_f32_32x32x16_bf16 v[16:31], v[186:189], v[84:87], v[16:31]
	v_exp_f32_e32 v71, v76
	v_exp_f32_e32 v72, v77
	v_add_f32_e32 v73, v71, v70
	v_cvt_pk_bf16_f32 v70, v71, v72
	v_add_f32_e32 v71, v72, v73
	v_mfma_f32_32x32x16_bf16 v[0:15], v[190:193], v[80:83], v[0:15]
	v_exp_f32_e32 v72, v78
	v_exp_f32_e32 v73, v79
	v_add_f32_e32 v74, v72, v71
	v_cvt_pk_bf16_f32 v71, v72, v73
	v_add_f32_e32 v198, v73, v74
	v_exp_f32_e32 v88, v100
	v_exp_f32_e32 v89, v101
	s_nop 0
	v_add_f32_e32 v165, v89, v88
	v_cvt_pk_bf16_f32 v164, v88, v89
	v_mfma_f32_32x32x16_bf16 v[0:15], v[194:197], v[84:87], v[0:15]
	ds_read_b128 v[72:75], v168 offset:23040
	ds_read_b128 v[76:79], v168 offset:23072
	ds_read_b128 v[80:83], v168 offset:23104
	v_cmp_nge_f32_e32 vcc, s62, v198
	ds_read_b128 v[84:87], v168 offset:23136
	v_exp_f32_e32 v166, v102
	v_exp_f32_e32 v167, v103
	s_waitcnt lgkmcnt(1)
	v_mfma_f32_32x32x16_bf16 v[88:103], v[72:75], v[116:119], 0
	ds_read_b128 v[178:181], v168 offset:27648
	ds_read_b128 v[186:189], v168 offset:27680
	ds_read_b128 v[190:193], v168 offset:32256
	ds_read_b128 v[194:197], v168 offset:32288
	v_add_f32_e32 v72, v166, v165
	v_add_f32_e32 v72, v167, v72
	v_cvt_pk_bf16_f32 v165, v166, v167
	v_mfma_f32_32x32x16_bf16 v[88:103], v[76:79], v[120:123], v[88:103]
	v_exp_f32_e32 v73, v104
	v_exp_f32_e32 v74, v105
	v_add_f32_e32 v72, v73, v72
	v_cvt_pk_bf16_f32 v166, v73, v74
	v_add_f32_e32 v72, v74, v72
	v_mfma_f32_32x32x16_bf16 v[88:103], v[80:83], v[124:127], v[88:103]
	v_exp_f32_e32 v73, v106
	v_exp_f32_e32 v74, v107
	v_add_f32_e32 v72, v73, v72
	v_cvt_pk_bf16_f32 v167, v73, v74
	v_add_f32_e32 v72, v74, v72
	s_waitcnt lgkmcnt(4)
	v_mfma_f32_32x32x16_bf16 v[88:103], v[84:87], v[128:131], v[88:103]
	v_exp_f32_e32 v73, v108
	v_exp_f32_e32 v74, v109
	v_add_f32_e32 v75, v73, v72
	v_cvt_pk_bf16_f32 v72, v73, v74
	v_add_f32_e32 v73, v74, v75
	s_waitcnt lgkmcnt(0)
	v_mfma_f32_32x32x16_bf16 v[48:63], v[178:181], v[64:67], v[48:63]
	v_exp_f32_e32 v74, v110
	v_exp_f32_e32 v75, v111
	v_add_f32_e32 v76, v74, v73
	v_cvt_pk_bf16_f32 v73, v74, v75
	v_add_f32_e32 v74, v75, v76
	v_mfma_f32_32x32x16_bf16 v[48:63], v[186:189], v[68:71], v[48:63]
	v_exp_f32_e32 v75, v112
	v_exp_f32_e32 v76, v113
	v_add_f32_e32 v77, v75, v74
	v_cvt_pk_bf16_f32 v74, v75, v76
	v_add_f32_e32 v75, v76, v77
	v_mfma_f32_32x32x16_bf16 v[32:47], v[190:193], v[64:67], v[32:47]
	v_exp_f32_e32 v76, v114
	v_exp_f32_e32 v77, v115
	v_add_f32_e32 v78, v76, v75
	v_cvt_pk_bf16_f32 v75, v76, v77
	v_add_f32_e32 v199, v77, v78
	v_exp_f32_e32 v76, v88
	v_exp_f32_e32 v77, v89
	s_nop 0
	v_add_f32_e32 v113, v77, v76
	v_cvt_pk_bf16_f32 v112, v76, v77
	v_mfma_f32_32x32x16_bf16 v[32:47], v[194:197], v[68:71], v[32:47]
	ds_read_b128 v[64:67], v168 offset:23040
	ds_read_b128 v[104:107], v168 offset:23072
	ds_read_b128 v[108:111], v168 offset:23104
	s_or_b64 s[6:7], s[4:5], vcc
	v_cmp_nge_f32_e32 vcc, s62, v199
	v_add_f32_e32 v182, v182, v198
	v_add_f32_e32 v183, v183, v199
	ds_read_b128 v[68:71], v168 offset:23136
	v_exp_f32_e32 v114, v90
	v_exp_f32_e32 v115, v91
	s_waitcnt lgkmcnt(1)
; template <int MODE, bool FAST> __device__ __forceinline__ bool attn_unit(LAS unsigned char* lds, const AttU& U, const int wv) {
;     ...
;         for (int t2 = U.kt0; t2 < U.kt1; t2 += 2) { ATT_TILE(t2, 4, rk, rr, rv); ATT_TILE(t2 + 1, 4, rk2, rr2, rv2); }
	v_mfma_f32_32x32x16_bf16 v[76:91], v[64:67], v[148:151], 0
	ds_read_b128 v[178:181], v168 offset:27648
	ds_read_b128 v[186:189], v168 offset:27680
	ds_read_b128 v[190:193], v168 offset:32256
	ds_read_b128 v[194:197], v168 offset:32288
	v_add_f32_e32 v64, v114, v113
	v_add_f32_e32 v64, v115, v64
	v_cvt_pk_bf16_f32 v113, v114, v115
	v_mfma_f32_32x32x16_bf16 v[76:91], v[104:107], v[152:155], v[76:91]
	v_exp_f32_e32 v65, v92
	v_exp_f32_e32 v66, v93
	v_add_f32_e32 v64, v65, v64
	v_cvt_pk_bf16_f32 v114, v65, v66
	v_add_f32_e32 v64, v66, v64
	v_mfma_f32_32x32x16_bf16 v[76:91], v[108:111], v[156:159], v[76:91]
	v_exp_f32_e32 v65, v94
	v_exp_f32_e32 v66, v95
	v_add_f32_e32 v64, v65, v64
	v_cvt_pk_bf16_f32 v115, v65, v66
	v_add_f32_e32 v64, v66, v64
	s_waitcnt lgkmcnt(4)
	v_mfma_f32_32x32x16_bf16 v[76:91], v[68:71], v[160:163], v[76:91]
	v_exp_f32_e32 v65, v96
	v_exp_f32_e32 v66, v97
	v_add_f32_e32 v64, v65, v64
	v_cvt_pk_bf16_f32 v92, v65, v66
	v_add_f32_e32 v64, v66, v64
	s_waitcnt lgkmcnt(0)
	v_mfma_f32_32x32x16_bf16 v[16:31], v[178:181], v[164:167], v[16:31]
	v_exp_f32_e32 v65, v98
	v_exp_f32_e32 v66, v99
	v_add_f32_e32 v64, v65, v64
	v_cvt_pk_bf16_f32 v93, v65, v66
	v_add_f32_e32 v64, v66, v64
	v_mfma_f32_32x32x16_bf16 v[16:31], v[186:189], v[72:75], v[16:31]
	v_exp_f32_e32 v65, v100
	v_exp_f32_e32 v66, v101
	v_add_f32_e32 v64, v65, v64
	v_cvt_pk_bf16_f32 v94, v65, v66
	v_add_f32_e32 v64, v66, v64
	v_mfma_f32_32x32x16_bf16 v[0:15], v[190:193], v[164:167], v[0:15]
	v_exp_f32_e32 v65, v102
	v_exp_f32_e32 v66, v103
	v_add_f32_e32 v64, v65, v64
	v_cvt_pk_bf16_f32 v95, v65, v66
	v_add_f32_e32 v198, v66, v64
	s_mulk_i32 s8, 0x4800
	v_exp_f32_e32 v68, v76
	v_exp_f32_e32 v69, v77
	s_nop 0
	v_add_f32_e32 v97, v69, v68
	v_cvt_pk_bf16_f32 v96, v68, v69
	v_mfma_f32_32x32x16_bf16 v[0:15], v[194:197], v[72:75], v[0:15]
	v_add_u32_e32 v185, s8, v184
	ds_read_b128 v[64:67], v185
	ds_read_b128 v[100:103], v185 offset:32
	ds_read_b128 v[104:107], v185 offset:64
	v_cmp_nge_f32_e64 s[4:5], s62, v198
	ds_read_b128 v[108:111], v185 offset:96
	s_or_b64 s[6:7], s[6:7], vcc
	v_exp_f32_e32 v98, v78
	v_exp_f32_e32 v99, v79
	s_waitcnt lgkmcnt(1)
	v_mfma_f32_32x32x16_bf16 v[64:79], v[64:67], v[116:119], 0
	ds_read_b128 v[164:167], v168 offset:27712
	ds_read_b128 v[178:181], v168 offset:27744
	ds_read_b128 v[186:189], v168 offset:32320
	ds_read_b128 v[190:193], v168 offset:32352
	v_add_f32_e32 v97, v98, v97
	v_add_f32_e32 v168, v99, v97
	v_cvt_pk_bf16_f32 v97, v98, v99
	v_mfma_f32_32x32x16_bf16 v[64:79], v[100:103], v[120:123], v[64:79]
	v_exp_f32_e32 v80, v80
	v_exp_f32_e32 v81, v81
	v_add_f32_e32 v99, v80, v168
	v_cvt_pk_bf16_f32 v98, v80, v81
	v_add_f32_e32 v80, v81, v99
	v_mfma_f32_32x32x16_bf16 v[64:79], v[104:107], v[124:127], v[64:79]
	v_exp_f32_e32 v81, v82
	v_exp_f32_e32 v82, v83
	v_add_f32_e32 v80, v81, v80
	v_cvt_pk_bf16_f32 v99, v81, v82
	v_add_f32_e32 v80, v82, v80
	s_waitcnt lgkmcnt(4)
	v_mfma_f32_32x32x16_bf16 v[64:79], v[108:111], v[128:131], v[64:79]
	v_exp_f32_e32 v81, v84
	v_exp_f32_e32 v82, v85
	v_add_f32_e32 v80, v81, v80
	v_cvt_pk_bf16_f32 v100, v81, v82
	v_add_f32_e32 v80, v82, v80
	s_waitcnt lgkmcnt(0)
	v_mfma_f32_32x32x16_bf16 v[48:63], v[164:167], v[112:115], v[48:63]
	v_exp_f32_e32 v81, v86
	v_exp_f32_e32 v82, v87
	v_add_f32_e32 v80, v81, v80
	v_cvt_pk_bf16_f32 v101, v81, v82
	v_add_f32_e32 v80, v82, v80
	v_mfma_f32_32x32x16_bf16 v[48:63], v[178:181], v[92:95], v[48:63]
	v_exp_f32_e32 v81, v88
	v_exp_f32_e32 v82, v89
	v_add_f32_e32 v80, v81, v80
	v_cvt_pk_bf16_f32 v102, v81, v82
	v_add_f32_e32 v80, v82, v80
	v_mfma_f32_32x32x16_bf16 v[32:47], v[186:189], v[112:115], v[32:47]
	v_exp_f32_e32 v81, v90
	v_exp_f32_e32 v82, v91
	v_add_f32_e32 v80, v81, v80
	v_cvt_pk_bf16_f32 v103, v81, v82
	v_add_f32_e32 v199, v82, v80
	v_mfma_f32_32x32x16_bf16 v[32:47], v[190:193], v[92:95], v[32:47]
	ds_read_b128 v[80:83], v185
	ds_read_b128 v[108:111], v185 offset:32
	ds_read_b128 v[104:107], v185 offset:64
	s_or_b64 s[4:5], s[6:7], s[4:5]
	v_cmp_nge_f32_e32 vcc, s62, v199
	s_or_b64 s[4:5], s[4:5], vcc
	s_cmp_lg_u64 s[4:5], 0
	s_cselect_b64 s[4:5], -1, 0
	s_or_b64 s[42:43], s[42:43], s[4:5]
	v_add_f32_e32 v178, v182, v198
	v_add_f32_e32 v179, v183, v199
	s_add_u32 s46, s46, 0x8000
	s_addc_u32 s47, s47, 0
	s_barrier
	s_waitcnt lgkmcnt(0)
	s_and_b64 vcc, exec, s[44:45]
	s_cbranch_vccnz .LBB0_451
	s_mov_b32 s33, s14
	s_branch .LBB0_437

.LBB0_935:
	s_or_b64 s[6:7], s[8:9], s[6:7]
	v_add_f32_e32 v84, v204, v246
	v_add_f32_e32 v85, v205, v247
	s_or_b64 s[6:7], s[6:7], s[10:11]
	s_or_b64 s[6:7], s[6:7], s[12:13]
	v_add_f32_e32 v178, v84, v210
	v_add_f32_e32 v179, v85, v211
	s_xor_b32 s10, s77, 2
	v_add_u32_e32 v222, s78, v244
	v_exp_f32_e32 v64, v64
	v_exp_f32_e32 v65, v65
	s_nop 0
	v_add_f32_e32 v84, v65, v64
	v_cvt_pk_bf16_f32 v166, v64, v65
	v_exp_f32_e32 v64, v66
	ds_read_b128 v[204:207], v199 offset:22624
	ds_read_b128 v[208:211], v199 offset:22656
	ds_read_b128 v[218:221], v199 offset:22688
	v_exp_f32_e32 v65, v67
	v_add_f32_e32 v66, v64, v84
	v_mfma_f32_32x32x16_bf16 v[80:95], v[80:83], v[122:125], 0
	v_add_f32_e32 v66, v65, v66
	v_cvt_pk_bf16_f32 v167, v64, v65
	v_mfma_f32_32x32x16_bf16 v[80:95], v[182:185], v[126:129], v[80:95]
	v_exp_f32_e32 v64, v68
	v_exp_f32_e32 v65, v69
	v_add_f32_e32 v66, v64, v66
	v_add_f32_e32 v66, v65, v66
	v_cvt_pk_bf16_f32 v168, v64, v65
	v_mfma_f32_32x32x16_bf16 v[80:95], v[174:177], v[130:133], v[80:95]
	v_exp_f32_e32 v64, v70
	v_exp_f32_e32 v65, v71
	v_add_f32_e32 v66, v64, v66
	v_add_f32_e32 v174, v65, v66
	v_cvt_pk_bf16_f32 v169, v64, v65
	s_waitcnt lgkmcnt(0)
	v_mfma_f32_32x32x16_bf16 v[80:95], v[204:207], v[134:137], v[80:95]
	ds_read_b128 v[64:67], v222 offset:13376
	ds_read_b128 v[68:71], v222 offset:13408
	ds_read_b128 v[180:183], v222 offset:17984
	ds_read_b128 v[222:225], v222 offset:18016
	v_exp_f32_e32 v72, v72
	v_exp_f32_e32 v73, v73
	v_add_f32_e32 v174, v72, v174
	v_add_f32_e32 v175, v73, v174
	v_cvt_pk_bf16_f32 v174, v72, v73
	v_mfma_f32_32x32x16_bf16 v[80:95], v[208:211], v[154:157], v[80:95]
	v_exp_f32_e32 v72, v74
	v_exp_f32_e32 v73, v75
	v_add_f32_e32 v74, v72, v175
	v_add_f32_e32 v74, v73, v74
	v_cvt_pk_bf16_f32 v175, v72, v73
	v_mfma_f32_32x32x16_bf16 v[80:95], v[218:221], v[158:161], v[80:95]
	v_exp_f32_e32 v72, v76
	v_exp_f32_e32 v73, v77
	v_add_f32_e32 v74, v72, v74
	v_add_f32_e32 v74, v73, v74
	v_cvt_pk_bf16_f32 v176, v72, v73
	s_waitcnt lgkmcnt(0)
	v_mfma_f32_32x32x16_bf16 v[16:31], v[64:67], v[162:165], v[16:31]
	v_exp_f32_e32 v64, v78
	v_exp_f32_e32 v65, v79
	v_add_f32_e32 v66, v64, v74
	v_add_f32_e32 v204, v65, v66
	v_cvt_pk_bf16_f32 v177, v64, v65
	v_mfma_f32_32x32x16_bf16 v[0:15], v[180:183], v[162:165], v[0:15]
	ds_read_b128 v[64:67], v199 offset:29184
	ds_read_b128 v[180:183], v199 offset:29216
	ds_read_b128 v[208:211], v199 offset:29248
	v_cmp_nge_f32_e32 vcc, s48, v204
	v_mfma_f32_32x32x16_bf16 v[16:31], v[68:71], v[170:173], v[16:31]
	v_mfma_f32_32x32x16_bf16 v[0:15], v[222:225], v[170:173], v[0:15]
	v_mad_u32_u24 v68, v187, s69, v186
	v_add_u32_e32 v206, s76, v68
	v_exp_f32_e32 v68, v80
	v_exp_f32_e32 v69, v81
	s_nop 0
	v_add_f32_e32 v70, v69, v68
	v_cvt_pk_bf16_f32 v162, v68, v69
	v_exp_f32_e32 v80, v82
	ds_read_b128 v[170:173], v199 offset:29280
	ds_read_b128 v[218:221], v199 offset:29312
	ds_read_b128 v[222:225], v199 offset:29344
	v_exp_f32_e32 v81, v83
	v_add_f32_e32 v82, v80, v70
	s_waitcnt lgkmcnt(3)
	v_mfma_f32_32x32x16_bf16 v[64:79], v[64:67], v[98:101], 0
	v_add_f32_e32 v82, v81, v82
	v_cvt_pk_bf16_f32 v163, v80, v81
	v_mfma_f32_32x32x16_bf16 v[64:79], v[180:183], v[102:105], v[64:79]
	v_exp_f32_e32 v80, v84
	v_exp_f32_e32 v81, v85
	v_add_f32_e32 v82, v80, v82
	v_add_f32_e32 v82, v81, v82
	v_cvt_pk_bf16_f32 v164, v80, v81
	v_mfma_f32_32x32x16_bf16 v[64:79], v[208:211], v[106:109], v[64:79]
	v_exp_f32_e32 v80, v86
	v_exp_f32_e32 v81, v87
	v_add_f32_e32 v82, v80, v82
	v_add_f32_e32 v184, v81, v82
	v_cvt_pk_bf16_f32 v165, v80, v81
	s_waitcnt lgkmcnt(0)
	v_mfma_f32_32x32x16_bf16 v[64:79], v[170:173], v[110:113], v[64:79]
	ds_read_b128 v[80:83], v206 offset:35840
	ds_read_b128 v[84:87], v206 offset:35872
	ds_read_b128 v[180:183], v206 offset:40448
	ds_read_b128 v[208:211], v206 offset:40480
	v_exp_f32_e32 v88, v88
	v_exp_f32_e32 v89, v89
	v_add_f32_e32 v170, v88, v184
	v_add_f32_e32 v171, v89, v170
	v_cvt_pk_bf16_f32 v170, v88, v89
	v_mfma_f32_32x32x16_bf16 v[64:79], v[218:221], v[114:117], v[64:79]
	v_exp_f32_e32 v88, v90
	v_exp_f32_e32 v89, v91
	v_add_f32_e32 v90, v88, v171
	v_add_f32_e32 v90, v89, v90
	v_cvt_pk_bf16_f32 v171, v88, v89
	v_mfma_f32_32x32x16_bf16 v[64:79], v[222:225], v[118:121], v[64:79]
	v_exp_f32_e32 v88, v92
	v_exp_f32_e32 v89, v93
	v_add_f32_e32 v90, v88, v90
	v_add_f32_e32 v90, v89, v90
	v_cvt_pk_bf16_f32 v172, v88, v89
	s_waitcnt lgkmcnt(0)
	v_mfma_f32_32x32x16_bf16 v[48:63], v[80:83], v[166:169], v[48:63]
	v_exp_f32_e32 v80, v94
	v_exp_f32_e32 v81, v95
	v_add_f32_e32 v82, v80, v90
	v_add_f32_e32 v205, v81, v82
	v_cvt_pk_bf16_f32 v173, v80, v81
	v_mfma_f32_32x32x16_bf16 v[32:47], v[180:183], v[166:169], v[32:47]
	ds_read_b128 v[80:83], v199 offset:29184
	ds_read_b128 v[166:169], v199 offset:29216
	ds_read_b128 v[182:185], v199 offset:29248
	s_or_b64 s[8:9], s[6:7], vcc
	v_cmp_nge_f32_e32 vcc, s48, v205
	v_add_f32_e32 v204, v178, v204
	v_add_f32_e32 v205, v179, v205
	v_mfma_f32_32x32x16_bf16 v[48:63], v[84:87], v[174:177], v[48:63]
	v_exp_f32_e32 v64, v64
	v_exp_f32_e32 v65, v65
	s_nop 0
	v_add_f32_e32 v84, v65, v64
	v_cvt_pk_bf16_f32 v178, v64, v65
	v_exp_f32_e32 v64, v66
	v_exp_f32_e32 v65, v67
	v_add_f32_e32 v66, v64, v84
	v_mfma_f32_32x32x16_bf16 v[32:47], v[208:211], v[174:177], v[32:47]
	ds_read_b128 v[174:177], v199 offset:29280
	ds_read_b128 v[208:211], v199 offset:29312
	ds_read_b128 v[218:221], v199 offset:29344
	s_waitcnt lgkmcnt(3)
; template <int MODE, bool FAST> __device__ __forceinline__ bool attn_unit(LAS unsigned char* lds, const AttU& U, const int wv) {
;     ...
;     if constexpr (FAST) {
;         for (int t2 = U.kt0; t2 < U.kt1; t2 += 2) { ATT_TILE(t2, 4, rk, rr, rv); ATT_TILE(t2 + 1, 4, rk2, rr2, rv2); }
	v_mfma_f32_32x32x16_bf16 v[80:95], v[80:83], v[122:125], 0
	v_add_f32_e32 v66, v65, v66
	v_cvt_pk_bf16_f32 v179, v64, v65
	v_mfma_f32_32x32x16_bf16 v[80:95], v[166:169], v[126:129], v[80:95]
	v_exp_f32_e32 v64, v68
	v_exp_f32_e32 v65, v69
	v_add_f32_e32 v66, v64, v66
	v_add_f32_e32 v66, v65, v66
	v_cvt_pk_bf16_f32 v180, v64, v65
	v_mfma_f32_32x32x16_bf16 v[80:95], v[182:185], v[130:133], v[80:95]
	v_exp_f32_e32 v64, v70
	v_exp_f32_e32 v65, v71
	v_add_f32_e32 v66, v64, v66
	v_add_f32_e32 v182, v65, v66
	v_cvt_pk_bf16_f32 v181, v64, v65
	s_waitcnt lgkmcnt(0)
	v_mfma_f32_32x32x16_bf16 v[80:95], v[174:177], v[134:137], v[80:95]
	ds_read_b128 v[64:67], v206 offset:35840
	ds_read_b128 v[68:71], v206 offset:35872
	ds_read_b128 v[166:169], v206 offset:40448
	ds_read_b128 v[222:225], v206 offset:40480
	v_exp_f32_e32 v72, v72
	v_exp_f32_e32 v73, v73
	v_add_f32_e32 v174, v72, v182
	v_add_f32_e32 v174, v73, v174
	v_cvt_pk_bf16_f32 v182, v72, v73
	v_mfma_f32_32x32x16_bf16 v[80:95], v[208:211], v[154:157], v[80:95]
	v_exp_f32_e32 v72, v74
	v_exp_f32_e32 v73, v75
	v_add_f32_e32 v74, v72, v174
	v_add_f32_e32 v74, v73, v74
	v_cvt_pk_bf16_f32 v183, v72, v73
	v_mfma_f32_32x32x16_bf16 v[80:95], v[218:221], v[158:161], v[80:95]
	v_exp_f32_e32 v72, v76
	v_exp_f32_e32 v73, v77
	v_add_f32_e32 v74, v72, v74
	v_add_f32_e32 v74, v73, v74
	v_cvt_pk_bf16_f32 v184, v72, v73
	s_waitcnt lgkmcnt(0)
	v_mfma_f32_32x32x16_bf16 v[16:31], v[64:67], v[162:165], v[16:31]
	v_exp_f32_e32 v64, v78
	v_exp_f32_e32 v65, v79
	v_add_f32_e32 v66, v64, v74
	v_add_f32_e32 v226, v65, v66
	v_cvt_pk_bf16_f32 v185, v64, v65
	v_mfma_f32_32x32x16_bf16 v[0:15], v[166:169], v[162:165], v[0:15]
	s_mulk_i32 s10, 0x5800
	v_add_u32_e32 v199, s10, v242
	ds_read_b128 v[64:67], v199
	ds_read_b128 v[164:167], v199 offset:32
	ds_read_b128 v[174:177], v199 offset:64
	v_cmp_nge_f32_e64 s[6:7], s48, v226
	v_mfma_f32_32x32x16_bf16 v[16:31], v[68:71], v[170:173], v[16:31]
	v_exp_f32_e32 v68, v80
	v_exp_f32_e32 v69, v81
	s_nop 0
	v_add_f32_e32 v70, v69, v68
	v_cvt_pk_bf16_f32 v162, v68, v69
	v_exp_f32_e32 v80, v82
	v_exp_f32_e32 v81, v83
	v_add_f32_e32 v82, v80, v70
	v_mfma_f32_32x32x16_bf16 v[0:15], v[222:225], v[170:173], v[0:15]
	s_or_b64 s[8:9], s[8:9], vcc
	ds_read_b128 v[168:171], v199 offset:96
	ds_read_b128 v[208:211], v199 offset:128
	ds_read_b128 v[218:221], v199 offset:160
	s_waitcnt lgkmcnt(3)
	v_mfma_f32_32x32x16_bf16 v[64:79], v[64:67], v[98:101], 0
	v_add_f32_e32 v82, v81, v82
	v_cvt_pk_bf16_f32 v163, v80, v81
	v_mfma_f32_32x32x16_bf16 v[64:79], v[164:167], v[102:105], v[64:79]
	v_exp_f32_e32 v80, v84
	v_exp_f32_e32 v81, v85
	v_add_f32_e32 v82, v80, v82
	v_add_f32_e32 v82, v81, v82
	v_cvt_pk_bf16_f32 v164, v80, v81
	v_mfma_f32_32x32x16_bf16 v[64:79], v[174:177], v[106:109], v[64:79]
	v_exp_f32_e32 v80, v86
	v_exp_f32_e32 v81, v87
	v_add_f32_e32 v82, v80, v82
	v_add_f32_e32 v166, v81, v82
	v_cvt_pk_bf16_f32 v165, v80, v81
	s_waitcnt lgkmcnt(0)
	v_mfma_f32_32x32x16_bf16 v[64:79], v[168:171], v[110:113], v[64:79]
	ds_read_b128 v[80:83], v206 offset:35904
	ds_read_b128 v[84:87], v206 offset:35936
	ds_read_b128 v[222:225], v206 offset:40512
	ds_read_b128 v[246:249], v206 offset:40544
	v_exp_f32_e32 v88, v88
	v_exp_f32_e32 v89, v89
	v_add_f32_e32 v166, v88, v166
	v_add_f32_e32 v167, v89, v166
	v_cvt_pk_bf16_f32 v166, v88, v89
	v_mfma_f32_32x32x16_bf16 v[64:79], v[208:211], v[114:117], v[64:79]
	v_exp_f32_e32 v88, v90
	v_exp_f32_e32 v89, v91
	v_add_f32_e32 v90, v88, v167
	v_add_f32_e32 v90, v89, v90
	v_cvt_pk_bf16_f32 v167, v88, v89
	v_mfma_f32_32x32x16_bf16 v[64:79], v[218:221], v[118:121], v[64:79]
	v_exp_f32_e32 v88, v92
	v_exp_f32_e32 v89, v93
	v_add_f32_e32 v90, v88, v90
	v_add_f32_e32 v90, v89, v90
	v_cvt_pk_bf16_f32 v168, v88, v89
	s_waitcnt lgkmcnt(0)
	v_mfma_f32_32x32x16_bf16 v[48:63], v[80:83], v[178:181], v[48:63]
	v_exp_f32_e32 v80, v94
	v_exp_f32_e32 v81, v95
	v_add_f32_e32 v82, v80, v90
	v_add_f32_e32 v227, v81, v82
	v_cvt_pk_bf16_f32 v169, v80, v81
	v_mfma_f32_32x32x16_bf16 v[32:47], v[222:225], v[178:181], v[32:47]
	ds_read_b128 v[80:83], v199
	ds_read_b128 v[174:177], v199 offset:32
	ds_read_b128 v[170:173], v199 offset:64
	s_or_b64 s[6:7], s[8:9], s[6:7]
	v_cmp_nge_f32_e32 vcc, s48, v227
	s_or_b64 s[6:7], s[6:7], vcc
	s_cmp_lg_u64 s[6:7], 0
	s_cselect_b64 s[6:7], -1, 0
	s_or_b64 s[42:43], s[42:43], s[6:7]
	v_mfma_f32_32x32x16_bf16 v[48:63], v[84:87], v[182:185], v[48:63]
	v_add_f32_e64 v204, v204, v226
	v_add_f32_e64 v205, v205, v227
	s_add_u32 s40, s40, 0x40000
	s_mov_b64 s[6:7], 0x2000
	s_addc_u32 s41, s41, 0
	v_lshl_add_u64 v[202:203], v[202:203], 0, s[6:7]
	s_barrier
	s_waitcnt lgkmcnt(0)
	v_mfma_f32_32x32x16_bf16 v[32:47], v[246:249], v[182:185], v[32:47]
	s_and_b64 vcc, exec, s[44:45]
	s_cbranch_vccnz .LBB0_937
	s_mov_b32 s61, s30
	s_branch .LBB0_923
